# v36 plus P5 half retention unit: its first eight reads (Q fragments, first K|V tile) requested right after the decay loads instead of behind the decay wait and the log2_sigmoid expansion
# speedup vs baseline: 1.0002x; 1.0002x over previous
.LBB0_386:
	s_cmp_gt_u32 s3, 0x7f
	s_cbranch_scc1 .LBB0_390
	s_bfe_u32 s5, s3, 0x20001
	s_lshl_b32 s0, s5, 2
	v_readlane_b32 s8, v242, 0
	v_mov_b32_e32 v2, v0
	v_mov_b32_e32 v1, s0
	v_readlane_b32 s12, v242, 4
	v_readlane_b32 s13, v242, 5
	s_nop 4
	global_load_dword v3, v1, s[12:13]
	global_load_dword v6, v1, s[12:13] offset:16
	v_readlane_b32 s9, v242, 1
	s_mov_b32 s9, 0xbfb8aa3b
	v_readlane_b32 s10, v242, 2
	v_readlane_b32 s11, v242, 3
	s_mov_b32 s10, 0x42ce8ed0
	s_mov_b32 s11, 0xc2b17218
	v_mov_b32_e32 v7, 0x7f800000
	s_mov_b32 s12, 0x3f2aaaab
	s_mov_b32 s8, 0x3f317218
	v_mov_b32_e32 v8, 0x3ecc95a3
	s_mov_b32 s4, 0x7f800000
	s_mov_b32 s7, 0x33800000
	v_mov_b32_e32 v9, 0x3f2aaada
	s_lshl_b32 s0, s38, 7
	s_lshl_b32 s1, s3, 5
	s_and_b32 s0, s0, 0x80
	s_and_b32 s6, s1, 0xf00
	s_sub_i32 s6, s6, 0x800
	v_readfirstlane_b32 s3, v2
	v_and_b32_e32 v18, 15, v2
	s_add_i32 s1, s6, 0x800
	s_ashr_i32 s3, s3, 6
	s_mov_b32 s63, 0
	s_lshl_b32 s62, s5, 8
	v_mov_b32_e32 v79, 0
	v_and_b32_e32 v78, 48, v2
	v_ashrrev_i32_e32 v26, 4, v2
	v_bfe_u32 v19, v2, 4, 2
	v_and_b32_e32 v1, 63, v2
	s_lshl_b32 s98, s3, 4
	s_movk_i32 s99, 0x1400
	v_or_b32_e32 v160, s0, v18
	v_or_b32_e32 v160, s1, v160
	v_add_u32_e32 v160, s98, v160
	v_mov_b64_e32 v[162:163], s[68:69]
	v_mad_i64_i32 v[164:165], s[100:101], v160, s99, v[162:163]
	v_lshl_add_u64 v[164:165], v[164:165], 0, s[62:63]
	v_lshl_add_u64 v[164:165], v[164:165], 0, v[78:79]
	global_load_dwordx4 v[168:171], v[164:165], off
	global_load_dwordx4 v[172:175], v[164:165], off offset:64
	global_load_dwordx4 v[176:179], v[164:165], off offset:128
	global_load_dwordx4 v[180:183], v[164:165], off offset:192
	v_lshlrev_b32_e32 v166, 4, v2
	v_and_b32_e32 v166, 0xf0, v166
	v_mov_b32_e32 v167, 0
	v_add_u32_e32 v160, s1, v26
	v_mad_i64_i32 v[164:165], s[100:101], v160, s99, v[162:163]
	v_lshl_add_u64 v[164:165], v[164:165], 0, s[62:63]
	v_lshl_add_u64 v[164:165], v[164:165], 0, v[166:167]
	global_load_dwordx4 v[184:187], v[164:165], off offset:1024
	global_load_dwordx4 v[188:191], v[164:165], off offset:2048
	v_add_u32_e32 v160, 0x200, v2
	v_ashrrev_i32_e32 v160, 4, v160
	v_add_u32_e32 v160, s1, v160
	v_mad_i64_i32 v[164:165], s[100:101], v160, s99, v[162:163]
	v_lshl_add_u64 v[164:165], v[164:165], 0, s[62:63]
	v_lshl_add_u64 v[164:165], v[164:165], 0, v[166:167]
	global_load_dwordx4 v[192:195], v[164:165], off offset:1024
	global_load_dwordx4 v[196:199], v[164:165], off offset:2048
	v_lshlrev_b32_e32 v84, 4, v18
	v_mov_b32_e32 v85, v79
	s_mov_b64 s[64:65], 0x50000
	v_mov_b32_e32 v46, v79
	v_mov_b32_e32 v47, v79
	v_mov_b32_e32 v48, v79
	v_mov_b32_e32 v49, v79
	v_mov_b32_e32 v42, v79
	v_mov_b32_e32 v43, v79
	v_mov_b32_e32 v44, v79
	v_mov_b32_e32 v45, v79
	v_mov_b32_e32 v38, v79
	v_mov_b32_e32 v39, v79
	v_mov_b32_e32 v40, v79
	v_mov_b32_e32 v41, v79
	v_mov_b32_e32 v34, v79
	v_mov_b32_e32 v35, v79
	v_mov_b32_e32 v36, v79
	v_mov_b32_e32 v37, v79
	v_mov_b32_e32 v27, v79
	v_mov_b32_e32 v28, v79
	v_mov_b32_e32 v29, v79
	v_readlane_b32 s14, v242, 6
	v_readlane_b32 s15, v242, 7
	v_readlane_b32 s16, v242, 8
	v_readlane_b32 s17, v242, 9
	v_readlane_b32 s18, v242, 10
	v_readlane_b32 s19, v242, 11
	v_readlane_b32 s20, v242, 12
	v_readlane_b32 s21, v242, 13
	v_readlane_b32 s22, v242, 14
	v_readlane_b32 s23, v242, 15
	s_waitcnt vmcnt(9)
	v_mul_f32_e32 v4, 0xbfb8aa3b, v3
	v_fma_f32 v10, v3, s9, -v4
	v_rndne_f32_e32 v11, v4
	v_fmac_f32_e32 v10, 0xb2a5705f, v3
	v_sub_f32_e32 v4, v4, v11
	v_add_f32_e32 v4, v4, v10
	v_cvt_i32_f32_e32 v11, v11
	v_exp_f32_e32 v4, v4
	v_cmp_nlt_f32_e32 vcc, s10, v3
	s_waitcnt vmcnt(8)
	v_mul_f32_e32 v5, 0xbfb8aa3b, v6
	v_fma_f32 v12, v6, s9, -v5
	v_ldexp_f32 v4, v4, v11
	v_cndmask_b32_e32 v4, 0, v4, vcc
	v_cmp_ngt_f32_e32 vcc, s11, v3
	v_rndne_f32_e32 v13, v5
	v_fmac_f32_e32 v12, 0xb2a5705f, v6
	v_cndmask_b32_e32 v3, v7, v4, vcc
	v_sub_f32_e32 v5, v5, v13
	v_add_f32_e32 v11, 1.0, v3
	v_add_f32_e32 v10, v5, v12
	v_add_f32_e32 v12, -1.0, v11
	v_frexp_mant_f32_e32 v14, v11
	v_cvt_f64_f32_e32 v[4:5], v11
	v_sub_f32_e32 v15, v12, v11
	v_frexp_exp_i32_f64_e32 v4, v[4:5]
	v_cmp_gt_f32_e32 vcc, s12, v14
	v_sub_f32_e32 v12, v3, v12
	v_add_f32_e32 v5, 1.0, v15
	v_subbrev_co_u32_e32 v4, vcc, 0, v4, vcc
	v_add_f32_e32 v5, v12, v5
	v_sub_u32_e32 v12, 0, v4
	v_cvt_f32_i32_e32 v4, v4
	v_ldexp_f32 v11, v11, v12
	v_ldexp_f32 v5, v5, v12
	v_add_f32_e32 v12, -1.0, v11
	v_add_f32_e32 v14, 1.0, v11
	v_add_f32_e32 v15, 1.0, v12
	v_add_f32_e32 v16, -1.0, v14
	v_sub_f32_e32 v15, v11, v15
	v_sub_f32_e32 v11, v11, v16
	v_mul_f32_e32 v16, 0x3f317218, v4
	v_add_f32_e32 v15, v5, v15
	v_add_f32_e32 v5, v5, v11
	v_fma_f32 v11, v4, s8, -v16
	v_add_f32_e32 v17, v12, v15
	v_add_f32_e32 v20, v14, v5
	v_fmac_f32_e32 v11, 0xb102e308, v4
	v_sub_f32_e32 v4, v12, v17
	v_sub_f32_e32 v12, v14, v20
	v_rcp_f32_e32 v14, v20
	v_add_f32_e32 v21, v16, v11
	v_add_f32_e32 v5, v5, v12
	v_sub_f32_e32 v12, v21, v16
	v_sub_f32_e32 v11, v11, v12
	v_mul_f32_e32 v12, v17, v14
	v_add_f32_e32 v4, v15, v4
	v_mul_f32_e32 v15, v20, v12
	v_fma_f32 v16, v12, v20, -v15
	v_fmac_f32_e32 v16, v12, v5
	v_add_f32_e32 v22, v15, v16
	v_sub_f32_e32 v23, v17, v22
	v_sub_f32_e32 v15, v22, v15
	v_sub_f32_e32 v17, v17, v23
	v_sub_f32_e32 v15, v15, v16
	v_sub_f32_e32 v16, v17, v22
	v_add_f32_e32 v4, v4, v16
	v_add_f32_e32 v4, v15, v4
	v_add_f32_e32 v15, v23, v4
	v_mul_f32_e32 v16, v14, v15
	v_sub_f32_e32 v17, v23, v15
	v_mul_f32_e32 v22, v20, v16
	v_add_f32_e32 v4, v4, v17
	v_add_f32_e32 v17, v12, v16
	v_fma_f32 v20, v16, v20, -v22
	v_sub_f32_e32 v12, v17, v12
	v_fmac_f32_e32 v20, v16, v5
	v_sub_f32_e32 v5, v16, v12
	v_add_f32_e32 v12, v22, v20
	v_sub_f32_e32 v16, v12, v22
	v_sub_f32_e32 v22, v15, v12
	v_sub_f32_e32 v15, v15, v22
	v_sub_f32_e32 v12, v15, v12
	v_sub_f32_e32 v16, v16, v20
	v_add_f32_e32 v4, v4, v12
	v_add_f32_e32 v4, v16, v4
	v_add_f32_e32 v4, v22, v4
	v_mul_f32_e32 v4, v14, v4
	v_add_f32_e32 v4, v5, v4
	v_add_f32_e32 v5, v17, v4
	v_mul_f32_e32 v12, v5, v5
	v_fmamk_f32 v16, v12, 0x3e9b6dac, v8
	v_sub_f32_e32 v14, v5, v17
	v_ldexp_f32 v15, v5, 1
	v_mul_f32_e32 v5, v5, v12
	v_fmaak_f32 v12, v12, v16, 0x3f2aaada
	v_mul_f32_e32 v5, v5, v12
	v_add_f32_e32 v12, v15, v5
	v_sub_f32_e32 v4, v4, v14
	v_sub_f32_e32 v14, v12, v15
	v_ldexp_f32 v4, v4, 1
	v_sub_f32_e32 v5, v5, v14
	v_add_f32_e32 v4, v4, v5
	v_add_f32_e32 v5, v12, v4
	v_sub_f32_e32 v12, v5, v12
	v_add_f32_e32 v14, v21, v5
	v_sub_f32_e32 v4, v4, v12
	v_sub_f32_e32 v12, v14, v21
	v_sub_f32_e32 v15, v14, v12
	v_sub_f32_e32 v5, v5, v12
	v_add_f32_e32 v12, v11, v4
	v_sub_f32_e32 v15, v21, v15
	v_sub_f32_e32 v16, v12, v11
	v_add_f32_e32 v5, v5, v15
	v_sub_f32_e32 v15, v12, v16
	v_sub_f32_e32 v4, v4, v16
	v_sub_f32_e32 v11, v11, v15
	v_add_f32_e32 v5, v12, v5
	v_add_f32_e32 v4, v4, v11
	v_add_f32_e32 v11, v14, v5
	v_sub_f32_e32 v12, v11, v14
	v_sub_f32_e32 v5, v5, v12
	v_add_f32_e32 v4, v4, v5
	v_exp_f32_e32 v5, v10
	v_cvt_i32_f32_e32 v10, v13
	v_add_f32_e32 v4, v11, v4
	v_cmp_neq_f32_e32 vcc, s4, v3
	v_lshlrev_b32_e32 v20, 3, v19
	v_lshlrev_b32_e32 v21, 3, v2
	v_cndmask_b32_e32 v4, v7, v4, vcc
	v_cmp_lt_f32_e64 vcc, |v3|, s7
	s_nop 1
	v_cndmask_b32_e32 v3, v4, v3, vcc
	v_mul_f32_e32 v90, 0xbfb8aa3b, v3
	v_ldexp_f32 v3, v5, v10
	v_cmp_nlt_f32_e32 vcc, s10, v6
	s_movk_i32 s10, 0x1400
	v_exp_f32_e64 v95, -v90
	v_cndmask_b32_e32 v3, 0, v3, vcc
	v_cmp_ngt_f32_e32 vcc, s11, v6
	s_nop 1
	v_cndmask_b32_e32 v3, v7, v3, vcc
	v_add_f32_e32 v6, 1.0, v3
	v_add_f32_e32 v4, -1.0, v6
	v_sub_f32_e32 v5, v4, v6
	v_add_f32_e32 v5, 1.0, v5
	v_sub_f32_e32 v4, v3, v4
	v_add_f32_e32 v10, v4, v5
	v_frexp_mant_f32_e32 v11, v6
	v_cvt_f64_f32_e32 v[4:5], v6
	v_frexp_exp_i32_f64_e32 v4, v[4:5]
	v_cmp_gt_f32_e32 vcc, s12, v11
	s_nop 1
	v_subbrev_co_u32_e32 v4, vcc, 0, v4, vcc
	v_sub_u32_e32 v5, 0, v4
	v_ldexp_f32 v6, v6, v5
	v_ldexp_f32 v5, v10, v5
	v_add_f32_e32 v10, -1.0, v6
	v_add_f32_e32 v13, 1.0, v6
	v_add_f32_e32 v11, 1.0, v10
	v_add_f32_e32 v14, -1.0, v13
	v_sub_f32_e32 v11, v6, v11
	v_sub_f32_e32 v6, v6, v14
	v_add_f32_e32 v11, v5, v11
	v_add_f32_e32 v5, v5, v6
	v_add_f32_e32 v6, v13, v5
	v_rcp_f32_e32 v14, v6
	v_add_f32_e32 v12, v10, v11
	v_sub_f32_e32 v10, v10, v12
	v_add_f32_e32 v10, v11, v10
	v_sub_f32_e32 v11, v13, v6
	v_add_f32_e32 v5, v5, v11
	v_mul_f32_e32 v11, v12, v14
	v_mul_f32_e32 v13, v6, v11
	v_fma_f32 v15, v11, v6, -v13
	v_fmac_f32_e32 v15, v11, v5
	v_add_f32_e32 v16, v13, v15
	v_sub_f32_e32 v17, v12, v16
	v_sub_f32_e32 v12, v12, v17
	v_sub_f32_e32 v13, v16, v13
	v_sub_f32_e32 v12, v12, v16
	v_add_f32_e32 v10, v10, v12
	v_sub_f32_e32 v12, v13, v15
	v_add_f32_e32 v10, v12, v10
	v_add_f32_e32 v12, v17, v10
	v_mul_f32_e32 v13, v14, v12
	v_mul_f32_e32 v15, v6, v13
	v_fma_f32 v6, v13, v6, -v15
	v_fmac_f32_e32 v6, v13, v5
	v_sub_f32_e32 v5, v17, v12
	v_add_f32_e32 v5, v10, v5
	v_add_f32_e32 v10, v15, v6
	v_sub_f32_e32 v16, v12, v10
	v_sub_f32_e32 v12, v12, v16
	v_sub_f32_e32 v15, v10, v15
	v_sub_f32_e32 v10, v12, v10
	v_add_f32_e32 v5, v5, v10
	v_sub_f32_e32 v6, v15, v6
	v_add_f32_e32 v5, v6, v5
	v_add_f32_e32 v6, v11, v13
	v_add_f32_e32 v5, v16, v5
	v_sub_f32_e32 v10, v6, v11
	v_mul_f32_e32 v5, v14, v5
	v_sub_f32_e32 v10, v13, v10
	v_add_f32_e32 v5, v10, v5
	v_cvt_f32_i32_e32 v4, v4
	v_add_f32_e32 v10, v6, v5
	v_mul_f32_e32 v11, v10, v10
	v_fmac_f32_e32 v8, 0x3e9b6dac, v11
	v_fmac_f32_e32 v9, v11, v8
	v_mul_f32_e32 v8, 0x3f317218, v4
	v_fma_f32 v12, v4, s8, -v8
	v_fmac_f32_e32 v12, 0xb102e308, v4
	v_sub_f32_e32 v4, v10, v6
	v_sub_f32_e32 v4, v5, v4
	v_add_f32_e32 v5, v8, v12
	v_sub_f32_e32 v6, v5, v8
	v_ldexp_f32 v8, v10, 1
	v_mul_f32_e32 v10, v10, v11
	v_mul_f32_e32 v9, v10, v9
	v_add_f32_e32 v10, v8, v9
	v_sub_f32_e32 v8, v10, v8
	v_ldexp_f32 v4, v4, 1
	v_sub_f32_e32 v8, v9, v8
	v_add_f32_e32 v4, v4, v8
	v_add_f32_e32 v8, v10, v4
	v_sub_f32_e32 v9, v8, v10
	v_sub_f32_e32 v4, v4, v9
	v_add_f32_e32 v9, v5, v8
	v_sub_f32_e32 v10, v9, v5
	v_sub_f32_e32 v11, v9, v10
	v_sub_f32_e32 v6, v12, v6
	v_sub_f32_e32 v5, v5, v11
	v_sub_f32_e32 v8, v8, v10
	v_add_f32_e32 v5, v8, v5
	v_add_f32_e32 v8, v6, v4
	v_sub_f32_e32 v10, v8, v6
	v_sub_f32_e32 v11, v8, v10
	v_sub_f32_e32 v6, v6, v11
	v_sub_f32_e32 v4, v4, v10
	v_add_f32_e32 v5, v8, v5
	v_add_f32_e32 v4, v4, v6
	v_add_f32_e32 v6, v9, v5
	v_sub_f32_e32 v8, v6, v9
	v_sub_f32_e32 v5, v5, v8
	v_add_f32_e32 v4, v4, v5
	v_add_f32_e32 v4, v6, v4
	v_cmp_neq_f32_e32 vcc, s4, v3
	v_lshlrev_b32_e32 v8, 4, v2
	v_and_b32_e32 v8, 0xf0, v8
	v_cndmask_b32_e32 v4, v7, v4, vcc
	v_cmp_lt_f32_e64 vcc, |v3|, s7
	s_mul_i32 s7, s3, 0x1200
	s_lshl_b32 s3, s3, 4
	v_cndmask_b32_e32 v3, v4, v3, vcc
	v_mul_f32_e32 v99, 0xbfb8aa3b, v3
	v_mul_f32_e32 v3, 0x80000000, v90
	v_exp_f32_e32 v97, v3
	v_mul_f32_e32 v3, 0, v99
	v_exp_f32_e32 v98, v3
	v_mul_f32_e32 v3, -2.0, v90
	v_exp_f32_e32 v93, v3
	v_add_f32_e32 v3, v99, v99
	v_exp_f32_e32 v94, v3
	v_mul_f32_e32 v3, 0xc0400000, v90
	v_exp_f32_e32 v91, v3
	v_mul_f32_e32 v3, 0x40400000, v99
	v_exp_f32_e32 v92, v3
	v_or_b32_e32 v3, s0, v18
	v_or_b32_e32 v4, s1, v3
	v_add_u32_e32 v6, s3, v4
	v_mov_b64_e32 v[4:5], s[68:69]
	v_mad_i64_i32 v[6:7], s[8:9], v6, s10, v[4:5]
	v_lshl_add_u64 v[6:7], v[6:7], 0, s[62:63]
	v_lshl_add_u64 v[6:7], v[6:7], 0, v[78:79]
	v_add_u32_e32 v6, s1, v26
	v_mad_i64_i32 v[6:7], s[8:9], v6, s10, v[4:5]
	v_lshl_add_u64 v[6:7], v[6:7], 0, s[62:63]
	v_mov_b32_e32 v9, v79
	v_lshl_add_u64 v[6:7], v[6:7], 0, v[8:9]
	v_add_u32_e32 v6, 0x200, v2
	v_ashrrev_i32_e32 v6, 4, v6
	v_add_u32_e32 v7, s1, v6
	v_mad_i64_i32 v[4:5], s[8:9], v7, s10, v[4:5]
	v_lshl_add_u64 v[4:5], v[4:5], 0, s[62:63]
	v_lshl_add_u64 v[4:5], v[4:5], 0, v[8:9]
	s_waitcnt vmcnt(0)
	v_mov_b32_e32 v30, v168
	v_mov_b32_e32 v31, v169
	v_mov_b32_e32 v32, v170
	v_mov_b32_e32 v33, v171
	v_mov_b32_e32 v22, v172
	v_mov_b32_e32 v23, v173
	v_mov_b32_e32 v24, v174
	v_mov_b32_e32 v25, v175
	v_mov_b32_e32 v14, v176
	v_mov_b32_e32 v15, v177
	v_mov_b32_e32 v16, v178
	v_mov_b32_e32 v17, v179
	v_mov_b32_e32 v10, v180
	v_mov_b32_e32 v11, v181
	v_mov_b32_e32 v12, v182
	v_mov_b32_e32 v13, v183
	v_mov_b32_e32 v50, v184
	v_mov_b32_e32 v51, v185
	v_mov_b32_e32 v52, v186
	v_mov_b32_e32 v53, v187
	v_mov_b32_e32 v54, v188
	v_mov_b32_e32 v55, v189
	v_mov_b32_e32 v56, v190
	v_mov_b32_e32 v57, v191
	v_mov_b32_e32 v58, v192
	v_mov_b32_e32 v59, v193
	v_mov_b32_e32 v60, v194
	v_mov_b32_e32 v61, v195
	v_mov_b32_e32 v62, v196
	v_mov_b32_e32 v63, v197
	v_mov_b32_e32 v64, v198
	v_mov_b32_e32 v65, v199
	v_lshlrev_b32_e32 v7, 2, v19
	s_lshl_b32 s4, s5, 7
	s_add_i32 s5, s7, 0
	v_sub_u32_e32 v3, v3, v7
	v_bfe_u32 v2, v2, 2, 2
	v_add_u32_e32 v4, 0, v8
	v_add_u32_e32 v5, 0, v78
	v_add_u32_e32 v101, s3, v3
	v_mov_b32_e32 v3, s5
	v_or_b32_e32 v2, v20, v2
	s_movk_i32 s5, 0x110
	v_mul_u32_u24_e32 v9, 0x110, v2
	v_mad_u64_u32 v[82:83], s[8:9], v26, s5, v[4:5]
	v_mad_u64_u32 v[80:81], s[8:9], v6, s5, v[4:5]
	v_sub_u32_e32 v2, v7, v18
	s_movk_i32 s7, 0x90
	v_subrev_u32_e32 v2, s3, v2
	s_add_u32 s8, s54, s62
	v_mad_u32_u24 v102, v18, s7, v3
	v_and_b32_e32 v3, 24, v21
	v_subrev_u32_e32 v103, s0, v2
	v_add_u32_e32 v2, s6, v6
	s_addc_u32 s9, s55, 0
	v_exp_f32_e32 v96, v99
	v_add_u32_e32 v8, 0, v3
	v_add_u32_e32 v6, 0x840, v2
	v_mov_b64_e32 v[2:3], s[8:9]
	v_mad_i64_i32 v[86:87], s[8:9], v6, s10, v[2:3]
	v_add_u32_e32 v6, s6, v26
	v_mul_u32_u24_e32 v4, 0x110, v18
	v_add_u32_e32 v6, 0x840, v6
	v_add_u32_e32 v100, v102, v20
	v_add_u32_e32 v104, 49, v103
	v_add_u32_e32 v105, 50, v103
	v_add_u32_e32 v106, 51, v103
	v_add_u32_e32 v107, 33, v103
	v_add_u32_e32 v108, 34, v103
	v_add_u32_e32 v109, 35, v103
	v_add_u32_e32 v110, 17, v103
	v_add_u32_e32 v111, 18, v103
	v_add_u32_e32 v112, 19, v103
	v_add_u32_e32 v113, 3, v103
	v_add_u32_e32 v114, 2, v103
	v_add_u32_e32 v115, 1, v103
	v_mad_i64_i32 v[88:89], s[6:7], v6, s10, v[2:3]
	s_mov_b32 s5, 0x6400000
	v_add_u32_e32 v83, v5, v4
	v_add_u32_e32 v81, v8, v9
	s_mov_b32 s62, s63
	v_mov_b32_e32 v26, v79
	v_mov_b32_e32 v18, v79
	v_mov_b32_e32 v19, v79
	v_mov_b32_e32 v20, v79
	v_mov_b32_e32 v21, v79
	v_mov_b32_e32 v2, v79
	v_mov_b32_e32 v3, v79
	v_mov_b32_e32 v4, v79
	v_mov_b32_e32 v5, v79
	v_mov_b32_e32 v6, v79
	v_mov_b32_e32 v7, v79
	v_mov_b32_e32 v8, v79
	v_mov_b32_e32 v9, v79
